# state_scan inner loop rewritten with prefetched batches; GEMM epilogue ss loads hoisted; M1/M3 loads de-serialized
# baseline (speedup 1.0000x reference)
; #define LAS __attribute__((address_space(3)))
; DI KA get_ka() { KA p = (KA)__builtin_amdgcn_kernarg_segment_ptr(); asm volatile("" : "+s"(p)); return p; }
; __global__ void __launch_bounds__(512, 2) hymba_fwd(Args a_unused) {
;     extern __shared__ __attribute__((aligned(16))) unsigned char lds_raw[];
;     LAS unsigned char* lds = (LAS unsigned char*)lds_raw;
;     cg::grid_group grid = cg::this_grid();
;     if (gridDim.x == 0x7fffffffu) grid.sync();
;     volatile LAS unsigned* bst = (volatile LAS unsigned*)(lds + 147200);
;     if (threadIdx.x < 2) bst[threadIdx.x] = 0u;
;     __syncthreads();
;     (void)xcd_barrier_post((unsigned*)(get_ka()->ws), bst);
;     ...
;     for (int rep = 0; rep < REP_PRO; ++rep) { prologue(get_ka(), lds); __syncthreads(); }
_Z9hymba_fwd4Args:
	s_mov_b32 s100, 0
	s_load_dwordx2 s[52:53], s[0:1], 0xe0
	v_writelane_b32 v254, s2, 0
	s_add_u32 s2, s0, 0xe0
	s_addc_u32 s3, s1, 0
	s_waitcnt lgkmcnt(0)
	s_cmp_eq_u32 s52, 0x7fffffff
	s_cbranch_scc1 .LBB0_2
	v_and_b32_e32 v212, 0x3ff, v0
	s_load_dword s26, s[0:1], 0xe8
	s_cbranch_execz .LBB0_3
	s_branch .LBB0_14

; DI KA get_ka() { KA p = (KA)__builtin_amdgcn_kernarg_segment_ptr(); asm volatile("" : "+s"(p)); return p; }
; DI int opaque_tid() { int t = threadIdx.x; asm volatile("" : "+v"(t)); return t; }
; __global__ void __launch_bounds__(512, 2) hymba_fwd(Args a_unused) {
;     ...
;     {
;         const KA a = get_ka();
;         const int tid = opaque_tid(), wave = tid >> 6, lane = tid & 63, G = gridDim.x;
;         const float* nf = a->in[25];
;         const float* ssf = (const float*)(a->ws + WS_SS) + 6 * MPAD;
;         const bf16_t* XB = (const bf16_t*)(a->ws + WS_XB);
;         float* out = a->out;
;         for (int rowb = blockIdx.x * 8 + wave; rowb < MTOK; rowb += 2 * G * 8) {
.LBB0_1530:
.Lrep_s0:
	v_readlane_b32 s2, v254, 4
	v_readlane_b32 s3, v254, 5
	v_readlane_b32 s0, v254, 59
	v_ashrrev_i32_e32 v0, 6, v212
	s_movk_i32 s12, 0x4480
	v_add_u32_e32 v0, s0, v0
	v_cmp_gt_i32_e32 vcc, s12, v0
	s_and_saveexec_b64 s[0:1], vcc
	s_cbranch_execz .LBB0_1553
	s_load_dwordx4 s[4:7], s[2:3], 0xd0
	s_load_dwordx2 s[0:1], s[2:3], 0xc8
	v_and_b32_e32 v1, 63, v212
	v_mov_b32_e32 v17, 0
	v_lshlrev_b32_e32 v16, 4, v1
	s_waitcnt lgkmcnt(0)
	s_add_u32 s2, s6, 0x167800
	s_addc_u32 s3, s7, 0
	v_lshl_add_u64 v[2:3], s[6:7], 0, v[16:17]
	v_lshlrev_b32_e32 v16, 5, v1
	s_add_u32 s8, s4, 0x4000000
	s_mov_b64 s[6:7], 0x2d00000
	v_lshl_add_u64 v[22:23], s[0:1], 0, v[16:17]
	v_readlane_b32 s0, v254, 12
	v_mov_b32_e32 v16, v17
	s_addc_u32 s9, s5, 0
	v_lshl_add_u64 v[18:19], v[2:3], 0, s[6:7]
	v_lshlrev_b32_e32 v20, 3, v1
	v_add_u32_e32 v24, 0xffffbf80, v0
	s_lshl_b32 s13, s0, 4
	s_mov_b32 s14, 0
	s_mov_b64 s[6:7], 0
	s_movk_i32 s15, 0x407f
	s_mov_b32 s16, 0xfe03f81
	s_movk_i32 s17, 0xf7f0
	v_mov_b32_e32 v21, 0x358637bd
	s_mov_b32 s18, 0x800000
	s_movk_i32 s19, 0x447f
	v_mov_b64_e32 v[26:27], v[16:17]
	v_readlane_b32 s1, v254, 13
	s_branch .LBB0_1533

; __global__ void __launch_bounds__(512, 2) hymba_fwd(Args a_unused) {
;     ...
;         }
;     }
.LBB0_1553:
	s_xor_b32 s100, s100, 1
	s_cmp_lg_u32 s100, 0
	s_cbranch_scc0 .Lrep_d0
	s_mov_b64 exec, -1
	s_branch .Lrep_s0

; __global__ void __launch_bounds__(512, 2) hymba_fwd(Args a_unused) {
	.amdhsa_kernel _Z9hymba_fwd4Args
		.amdhsa_group_segment_fixed_size 0
		.amdhsa_private_segment_fixed_size 0
		.amdhsa_kernarg_size 480
		.amdhsa_user_sgpr_count 2
		.amdhsa_user_sgpr_dispatch_ptr 0
		.amdhsa_user_sgpr_queue_ptr 0
		.amdhsa_user_sgpr_kernarg_segment_ptr 1
		.amdhsa_user_sgpr_dispatch_id 0
		.amdhsa_user_sgpr_kernarg_preload_length 0
		.amdhsa_user_sgpr_kernarg_preload_offset 0
		.amdhsa_user_sgpr_private_segment_size 0
		.amdhsa_uses_dynamic_stack 0
		.amdhsa_enable_private_segment 0
		.amdhsa_system_sgpr_workgroup_id_x 1
		.amdhsa_system_sgpr_workgroup_id_y 0
		.amdhsa_system_sgpr_workgroup_id_z 0
		.amdhsa_system_sgpr_workgroup_info 0
		.amdhsa_system_vgpr_workitem_id 2
		.amdhsa_next_free_vgpr 256
		.amdhsa_next_free_sgpr 102
		.amdhsa_accum_offset 256
		.amdhsa_reserve_vcc 1
		.amdhsa_float_round_mode_32 0
		.amdhsa_float_round_mode_16_64 0
		.amdhsa_float_denorm_mode_32 3
		.amdhsa_float_denorm_mode_16_64 3
		.amdhsa_dx10_clamp 1
		.amdhsa_ieee_mode 1
		.amdhsa_fp16_overflow 0
		.amdhsa_tg_split 0
		.amdhsa_exception_fp_ieee_invalid_op 0
		.amdhsa_exception_fp_denorm_src 0
		.amdhsa_exception_fp_ieee_div_zero 0
		.amdhsa_exception_fp_ieee_overflow 0
		.amdhsa_exception_fp_ieee_underflow 0
		.amdhsa_exception_fp_ieee_inexact 0
		.amdhsa_exception_int_div_zero 0
	.end_amdhsa_kernel

; __global__ void __launch_bounds__(512, 2) hymba_fwd(Args a_unused) {
amdhsa.kernels:
  - .agpr_count:     0
    .args:
      - .offset:         0
        .size:           224
        .value_kind:     by_value
      - .offset:         224
        .size:           4
        .value_kind:     hidden_block_count_x
      - .offset:         228
        .size:           4
        .value_kind:     hidden_block_count_y
      - .offset:         232
        .size:           4
        .value_kind:     hidden_block_count_z
      - .offset:         236
        .size:           2
        .value_kind:     hidden_group_size_x
      - .offset:         238
        .size:           2
        .value_kind:     hidden_group_size_y
      - .offset:         240
        .size:           2
        .value_kind:     hidden_group_size_z
      - .offset:         242
        .size:           2
        .value_kind:     hidden_remainder_x
      - .offset:         244
        .size:           2
        .value_kind:     hidden_remainder_y
      - .offset:         246
        .size:           2
        .value_kind:     hidden_remainder_z
      - .offset:         264
        .size:           8
        .value_kind:     hidden_global_offset_x
      - .offset:         272
        .size:           8
        .value_kind:     hidden_global_offset_y
      - .offset:         280
        .size:           8
        .value_kind:     hidden_global_offset_z
      - .offset:         288
        .size:           2
        .value_kind:     hidden_grid_dims
      - .offset:         312
        .size:           8
        .value_kind:     hidden_multigrid_sync_arg
      - .offset:         344
        .size:           4
        .value_kind:     hidden_dynamic_lds_size
    .group_segment_fixed_size: 0
    .kernarg_segment_align: 8
    .kernarg_segment_size: 480
    .language:       OpenCL C
    .language_version:
      - 2
      - 0
    .max_flat_workgroup_size: 512
    .name:           _Z9hymba_fwd4Args
    .private_segment_fixed_size: 0
    .sgpr_count:     108
    .sgpr_spill_count: 104
    .symbol:         _Z9hymba_fwd4Args.kd
    .uniform_work_group_size: 1
    .uses_dynamic_stack: false
    .vgpr_count:     256
    .vgpr_spill_count: 0
    .wavefront_size: 64
